# attention pipelined stage: PV/QK MFMAs spaced inside the exp-heavy part of the softmax stream (cost-weighted spacing)
# baseline (speedup 1.0000x reference)
.LBB0_468:
	s_bitcmp1_b32 s1, 0
	s_cselect_b32 s2, 0x4800, 0
	s_add_i32 s2, s2, 0
	s_mov_b32 s1, 0
	v_add_u32_e32 v211, s2, v177
	v_add3_u32 v212, s2, v179, v181
	v_mad_u32_u24 v242, v204, s87, v211
	v_mov_b32_e32 v243, v212
	v_mov_b32_e32 v232, v210
	v_mov_b32_e32 v233, v213
	ds_read_b128 v[148:151], v242
	ds_read_b128 v[144:147], v242 offset:16
	ds_read_b128 v[136:139], v242 offset:32
	ds_read_b128 v[140:143], v242 offset:48
	ds_read_b128 v[132:135], v243 offset:9216
	ds_read_b128 v[128:131], v243 offset:9248
	ds_read_b128 v[124:127], v243 offset:13824
	ds_read_b128 v[120:123], v243 offset:13856
	s_waitcnt lgkmcnt(4)
	v_mfma_f32_32x32x16_bf16 v[64:79], v[148:151], v[96:99], 0
	v_mfma_f32_32x32x16_bf16 v[64:79], v[144:147], v[112:115], v[64:79]
	v_mfma_f32_32x32x16_bf16 v[64:79], v[136:139], v[100:103], v[64:79]
	v_mfma_f32_32x32x16_bf16 v[64:79], v[140:143], v[116:119], v[64:79]
	s_nop 11
	v_max_f32_e32 v234, v65, v65
	v_max_f32_e32 v235, v64, v64
	v_max_f32_e32 v234, v235, v234
	v_max3_f32 v234, v234, v66, v67
	v_max3_f32 v234, v234, v68, v69
	v_max3_f32 v234, v234, v70, v71
	v_max3_f32 v234, v234, v72, v73
	v_max3_f32 v234, v234, v74, v75
	v_max3_f32 v234, v234, v76, v77
	v_max3_f32 v234, v234, v78, v79
	v_mov_b32_e32 v235, v234
	s_nop 1
	v_permlane32_swap_b32_e32 v234, v235
	v_max_f32_e32 v235, v235, v235
	v_max_f32_e32 v234, v234, v234
	v_max_f32_e32 v234, v234, v235
	v_mul_f32_e32 v234, 0x3e38aa3b, v234
	v_add_f32_e32 v235, 0x41000000, v232
	v_cmp_gt_f32_e32 vcc, v234, v235
	s_nop 1
	v_cndmask_b32_e32 v238, v232, v234, vcc
	v_fma_f32 v64, v64, s77, -v238
	v_exp_f32_e32 v64, v64
	v_fma_f32 v65, v65, s77, -v238
	v_exp_f32_e32 v65, v65
	v_add_f32_e32 v236, 0, v64
	v_fma_f32 v66, v66, s77, -v238
	v_exp_f32_e32 v66, v66
	v_add_f32_e32 v236, v65, v236
	v_fma_f32 v67, v67, s77, -v238
	v_exp_f32_e32 v67, v67
	v_add_f32_e32 v236, v66, v236
	v_fma_f32 v68, v68, s77, -v238
	v_exp_f32_e32 v68, v68
	v_add_f32_e32 v236, v67, v236
	v_fma_f32 v69, v69, s77, -v238
	v_exp_f32_e32 v69, v69
	v_add_f32_e32 v236, v68, v236
	v_fma_f32 v70, v70, s77, -v238
	v_exp_f32_e32 v70, v70
	v_add_f32_e32 v236, v69, v236
	v_fma_f32 v71, v71, s77, -v238
	v_exp_f32_e32 v71, v71
	v_add_f32_e32 v236, v70, v236
	v_fma_f32 v72, v72, s77, -v238
	v_exp_f32_e32 v72, v72
	v_mfma_f32_32x32x16_bf16 v[216:231], v[148:151], v[104:107], 0
	v_add_f32_e32 v236, v71, v236
	v_fma_f32 v73, v73, s77, -v238
	v_exp_f32_e32 v73, v73
	v_add_f32_e32 v236, v72, v236
	v_fma_f32 v74, v74, s77, -v238
	v_exp_f32_e32 v74, v74
	v_mfma_f32_32x32x16_bf16 v[216:231], v[144:147], v[88:91], v[216:231]
	v_add_f32_e32 v236, v73, v236
	v_fma_f32 v75, v75, s77, -v238
	v_exp_f32_e32 v75, v75
	v_add_f32_e32 v236, v74, v236
	v_fma_f32 v76, v76, s77, -v238
	v_exp_f32_e32 v76, v76
	v_mfma_f32_32x32x16_bf16 v[216:231], v[136:139], v[108:111], v[216:231]
	v_add_f32_e32 v236, v75, v236
	v_fma_f32 v77, v77, s77, -v238
	v_exp_f32_e32 v77, v77
	v_add_f32_e32 v236, v76, v236
	v_fma_f32 v78, v78, s77, -v238
	v_exp_f32_e32 v78, v78
	v_mfma_f32_32x32x16_bf16 v[216:231], v[140:143], v[92:95], v[216:231]
	v_add_f32_e32 v236, v77, v236
	v_fma_f32 v79, v79, s77, -v238
	v_exp_f32_e32 v79, v79
	v_add_f32_e32 v236, v78, v236
	v_cmp_neq_f32_e32 vcc, v238, v232
	v_add_f32_e32 v236, v79, v236
	ds_read_b128 v[148:151], v242 offset:4608
	ds_read_b128 v[144:147], v242 offset:4624
	ds_read_b128 v[136:139], v242 offset:4640
	ds_read_b128 v[140:143], v242 offset:4656
	v_mov_b32_e32 v237, v236
	s_nop 1
	v_permlane32_swap_b32_e32 v236, v237
	s_cbranch_vccz .Lat_k0
	v_sub_f32_e32 v240, v232, v238
	v_exp_f32_e32 v240, v240
	s_nop 0
	v_mul_f32_e32 v207, v207, v240
	v_pk_mul_f32 v[32:33], v[32:33], v[240:241] op_sel_hi:[1,0]
	v_pk_mul_f32 v[34:35], v[34:35], v[240:241] op_sel_hi:[1,0]
	v_pk_mul_f32 v[36:37], v[36:37], v[240:241] op_sel_hi:[1,0]
	v_pk_mul_f32 v[38:39], v[38:39], v[240:241] op_sel_hi:[1,0]
	v_pk_mul_f32 v[40:41], v[40:41], v[240:241] op_sel_hi:[1,0]
	v_pk_mul_f32 v[42:43], v[42:43], v[240:241] op_sel_hi:[1,0]
	v_pk_mul_f32 v[44:45], v[44:45], v[240:241] op_sel_hi:[1,0]
	v_pk_mul_f32 v[46:47], v[46:47], v[240:241] op_sel_hi:[1,0]
	v_pk_mul_f32 v[48:49], v[48:49], v[240:241] op_sel_hi:[1,0]
	v_pk_mul_f32 v[50:51], v[50:51], v[240:241] op_sel_hi:[1,0]
	v_pk_mul_f32 v[52:53], v[52:53], v[240:241] op_sel_hi:[1,0]
	v_pk_mul_f32 v[54:55], v[54:55], v[240:241] op_sel_hi:[1,0]
	v_pk_mul_f32 v[56:57], v[56:57], v[240:241] op_sel_hi:[1,0]
	v_pk_mul_f32 v[58:59], v[58:59], v[240:241] op_sel_hi:[1,0]
	v_pk_mul_f32 v[60:61], v[60:61], v[240:241] op_sel_hi:[1,0]
	v_pk_mul_f32 v[62:63], v[62:63], v[240:241] op_sel_hi:[1,0]
.Lat_k0:
	v_cvt_pk_bf16_f32 v64, v64, v65
	v_cvt_pk_bf16_f32 v65, v66, v67
	v_cvt_pk_bf16_f32 v66, v68, v69
	v_cvt_pk_bf16_f32 v67, v70, v71
	v_cvt_pk_bf16_f32 v68, v72, v73
	v_cvt_pk_bf16_f32 v69, v74, v75
	v_cvt_pk_bf16_f32 v70, v76, v77
	v_cvt_pk_bf16_f32 v71, v78, v79
	v_add_f32_e32 v234, v236, v237
	v_add_f32_e32 v207, v234, v207
	v_mov_b32_e32 v232, v238
	v_max_f32_e32 v234, v217, v217
	v_max_f32_e32 v235, v216, v216
	v_max_f32_e32 v234, v235, v234
	v_max3_f32 v234, v234, v218, v219
	v_max3_f32 v234, v234, v220, v221
	v_max3_f32 v234, v234, v222, v223
	v_max3_f32 v234, v234, v224, v225
	v_max3_f32 v234, v234, v226, v227
	v_max3_f32 v234, v234, v228, v229
	v_max3_f32 v234, v234, v230, v231
	v_mov_b32_e32 v235, v234
	s_nop 1
	v_permlane32_swap_b32_e32 v234, v235
	v_max_f32_e32 v235, v235, v235
	v_max_f32_e32 v234, v234, v234
	v_max_f32_e32 v234, v234, v235
	v_mul_f32_e32 v234, 0x3e38aa3b, v234
	v_add_f32_e32 v235, 0x41000000, v233
	v_cmp_gt_f32_e32 vcc, v234, v235
	s_nop 1
	v_cndmask_b32_e32 v238, v233, v234, vcc
	v_fma_f32 v216, v216, s77, -v238
	s_waitcnt lgkmcnt(4)
	v_mfma_f32_32x32x16_bf16 v[48:63], v[132:135], v[64:67], v[48:63]
	v_exp_f32_e32 v216, v216
	v_fma_f32 v217, v217, s77, -v238
	v_exp_f32_e32 v217, v217
	v_add_f32_e32 v236, 0, v216
	v_fma_f32 v218, v218, s77, -v238
	v_exp_f32_e32 v218, v218
	v_mfma_f32_32x32x16_bf16 v[32:47], v[124:127], v[64:67], v[32:47]
	v_add_f32_e32 v236, v217, v236
	v_fma_f32 v219, v219, s77, -v238
	v_exp_f32_e32 v219, v219
	v_add_f32_e32 v236, v218, v236
	v_fma_f32 v220, v220, s77, -v238
	v_exp_f32_e32 v220, v220
	v_mfma_f32_32x32x16_bf16 v[48:63], v[128:131], v[68:71], v[48:63]
	v_add_f32_e32 v236, v219, v236
	v_fma_f32 v221, v221, s77, -v238
	v_exp_f32_e32 v221, v221
	v_add_f32_e32 v236, v220, v236
	v_fma_f32 v222, v222, s77, -v238
	v_exp_f32_e32 v222, v222
	v_mfma_f32_32x32x16_bf16 v[32:47], v[120:123], v[68:71], v[32:47]
	v_add_f32_e32 v236, v221, v236
	v_fma_f32 v223, v223, s77, -v238
	v_exp_f32_e32 v223, v223
	v_add_f32_e32 v236, v222, v236
	v_fma_f32 v224, v224, s77, -v238
	v_exp_f32_e32 v224, v224
	s_waitcnt lgkmcnt(0)
	v_mfma_f32_32x32x16_bf16 v[64:79], v[148:151], v[96:99], 0
	v_add_f32_e32 v236, v223, v236
	v_fma_f32 v225, v225, s77, -v238
	v_exp_f32_e32 v225, v225
	v_add_f32_e32 v236, v224, v236
	v_fma_f32 v226, v226, s77, -v238
	v_exp_f32_e32 v226, v226
	v_mfma_f32_32x32x16_bf16 v[64:79], v[144:147], v[112:115], v[64:79]
	v_add_f32_e32 v236, v225, v236
	v_fma_f32 v227, v227, s77, -v238
	v_exp_f32_e32 v227, v227
	v_add_f32_e32 v236, v226, v236
	v_fma_f32 v228, v228, s77, -v238
	v_exp_f32_e32 v228, v228
	v_mfma_f32_32x32x16_bf16 v[64:79], v[136:139], v[100:103], v[64:79]
	v_add_f32_e32 v236, v227, v236
	v_fma_f32 v229, v229, s77, -v238
	v_exp_f32_e32 v229, v229
	v_add_f32_e32 v236, v228, v236
	v_fma_f32 v230, v230, s77, -v238
	v_exp_f32_e32 v230, v230
	v_mfma_f32_32x32x16_bf16 v[64:79], v[140:143], v[116:119], v[64:79]
	v_add_f32_e32 v236, v229, v236
	v_fma_f32 v231, v231, s77, -v238
	v_exp_f32_e32 v231, v231
	v_add_f32_e32 v236, v230, v236
	v_cmp_neq_f32_e32 vcc, v238, v233
	v_add_f32_e32 v236, v231, v236
	v_mov_b32_e32 v237, v236
	s_nop 1
	v_permlane32_swap_b32_e32 v236, v237
	s_cbranch_vccz .Lat_k1
	v_sub_f32_e32 v240, v233, v238
	v_exp_f32_e32 v240, v240
	s_nop 0
	v_mul_f32_e32 v185, v185, v240
	v_pk_mul_f32 v[0:1], v[0:1], v[240:241] op_sel_hi:[1,0]
	v_pk_mul_f32 v[2:3], v[2:3], v[240:241] op_sel_hi:[1,0]
	v_pk_mul_f32 v[4:5], v[4:5], v[240:241] op_sel_hi:[1,0]
	v_pk_mul_f32 v[6:7], v[6:7], v[240:241] op_sel_hi:[1,0]
	v_pk_mul_f32 v[8:9], v[8:9], v[240:241] op_sel_hi:[1,0]
	v_pk_mul_f32 v[10:11], v[10:11], v[240:241] op_sel_hi:[1,0]
	v_pk_mul_f32 v[12:13], v[12:13], v[240:241] op_sel_hi:[1,0]
	v_pk_mul_f32 v[14:15], v[14:15], v[240:241] op_sel_hi:[1,0]
	v_pk_mul_f32 v[16:17], v[16:17], v[240:241] op_sel_hi:[1,0]
	v_pk_mul_f32 v[18:19], v[18:19], v[240:241] op_sel_hi:[1,0]
	v_pk_mul_f32 v[20:21], v[20:21], v[240:241] op_sel_hi:[1,0]
	v_pk_mul_f32 v[22:23], v[22:23], v[240:241] op_sel_hi:[1,0]
	v_pk_mul_f32 v[24:25], v[24:25], v[240:241] op_sel_hi:[1,0]
	v_pk_mul_f32 v[26:27], v[26:27], v[240:241] op_sel_hi:[1,0]
	v_pk_mul_f32 v[28:29], v[28:29], v[240:241] op_sel_hi:[1,0]
	v_pk_mul_f32 v[30:31], v[30:31], v[240:241] op_sel_hi:[1,0]
.Lat_k1:
	v_cvt_pk_bf16_f32 v216, v216, v217
	v_cvt_pk_bf16_f32 v217, v218, v219
	v_cvt_pk_bf16_f32 v218, v220, v221
	v_cvt_pk_bf16_f32 v219, v222, v223
	v_cvt_pk_bf16_f32 v220, v224, v225
	v_cvt_pk_bf16_f32 v221, v226, v227
	v_cvt_pk_bf16_f32 v222, v228, v229
	v_cvt_pk_bf16_f32 v223, v230, v231
	v_add_f32_e32 v234, v236, v237
	v_add_f32_e32 v185, v234, v185
	v_mov_b32_e32 v233, v238
	v_max_f32_e32 v234, v65, v65
	v_max_f32_e32 v235, v64, v64
	v_max_f32_e32 v234, v235, v234
	v_max3_f32 v234, v234, v66, v67
	v_max3_f32 v234, v234, v68, v69
	v_max3_f32 v234, v234, v70, v71
	v_max3_f32 v234, v234, v72, v73
	v_max3_f32 v234, v234, v74, v75
	v_max3_f32 v234, v234, v76, v77
	v_max3_f32 v234, v234, v78, v79
	v_mov_b32_e32 v235, v234
	s_nop 1
	v_permlane32_swap_b32_e32 v234, v235
	v_max_f32_e32 v235, v235, v235
	v_max_f32_e32 v234, v234, v234
	v_max_f32_e32 v234, v234, v235
	v_mul_f32_e32 v234, 0x3e38aa3b, v234
	v_add_f32_e32 v235, 0x41000000, v232
	v_cmp_gt_f32_e32 vcc, v234, v235
	s_nop 1
	v_cndmask_b32_e32 v238, v232, v234, vcc
	v_fma_f32 v64, v64, s77, -v238
	v_mfma_f32_32x32x16_bf16 v[16:31], v[132:135], v[216:219], v[16:31]
	v_exp_f32_e32 v64, v64
	v_fma_f32 v65, v65, s77, -v238
	v_exp_f32_e32 v65, v65
	v_add_f32_e32 v236, 0, v64
	v_fma_f32 v66, v66, s77, -v238
	v_exp_f32_e32 v66, v66
	v_mfma_f32_32x32x16_bf16 v[0:15], v[124:127], v[216:219], v[0:15]
	v_add_f32_e32 v236, v65, v236
	v_fma_f32 v67, v67, s77, -v238
	v_exp_f32_e32 v67, v67
	v_add_f32_e32 v236, v66, v236
	v_fma_f32 v68, v68, s77, -v238
	v_exp_f32_e32 v68, v68
	v_mfma_f32_32x32x16_bf16 v[16:31], v[128:131], v[220:223], v[16:31]
	v_add_f32_e32 v236, v67, v236
	v_fma_f32 v69, v69, s77, -v238
	v_exp_f32_e32 v69, v69
	v_add_f32_e32 v236, v68, v236
	v_fma_f32 v70, v70, s77, -v238
	v_exp_f32_e32 v70, v70
	v_mfma_f32_32x32x16_bf16 v[0:15], v[120:123], v[220:223], v[0:15]
	v_add_f32_e32 v236, v69, v236
	v_fma_f32 v71, v71, s77, -v238
	ds_read_b128 v[132:135], v243 offset:9280
	ds_read_b128 v[128:131], v243 offset:9312
	ds_read_b128 v[124:127], v243 offset:13888
	ds_read_b128 v[120:123], v243 offset:13920
	v_exp_f32_e32 v71, v71
	v_add_f32_e32 v236, v70, v236
	v_fma_f32 v72, v72, s77, -v238
	v_exp_f32_e32 v72, v72
	v_mfma_f32_32x32x16_bf16 v[216:231], v[148:151], v[104:107], 0
	v_add_f32_e32 v236, v71, v236
	v_fma_f32 v73, v73, s77, -v238
	v_exp_f32_e32 v73, v73
	v_add_f32_e32 v236, v72, v236
	v_fma_f32 v74, v74, s77, -v238
	v_exp_f32_e32 v74, v74
	v_mfma_f32_32x32x16_bf16 v[216:231], v[144:147], v[88:91], v[216:231]
	v_add_f32_e32 v236, v73, v236
	v_fma_f32 v75, v75, s77, -v238
	v_exp_f32_e32 v75, v75
	v_add_f32_e32 v236, v74, v236
	v_fma_f32 v76, v76, s77, -v238
	v_exp_f32_e32 v76, v76
	v_mfma_f32_32x32x16_bf16 v[216:231], v[136:139], v[108:111], v[216:231]
	v_add_f32_e32 v236, v75, v236
	v_fma_f32 v77, v77, s77, -v238
	v_exp_f32_e32 v77, v77
	v_add_f32_e32 v236, v76, v236
	v_fma_f32 v78, v78, s77, -v238
	v_exp_f32_e32 v78, v78
	v_mfma_f32_32x32x16_bf16 v[216:231], v[140:143], v[92:95], v[216:231]
	v_add_f32_e32 v236, v77, v236
	v_fma_f32 v79, v79, s77, -v238
	v_exp_f32_e32 v79, v79
	v_add_f32_e32 v236, v78, v236
	v_cmp_neq_f32_e32 vcc, v238, v232
	v_add_f32_e32 v236, v79, v236
	v_mov_b32_e32 v237, v236
	s_nop 1
	v_permlane32_swap_b32_e32 v236, v237
	s_cbranch_vccz .Lat_k2
	v_sub_f32_e32 v240, v232, v238
	v_exp_f32_e32 v240, v240
	s_nop 0
	v_mul_f32_e32 v207, v207, v240
	v_pk_mul_f32 v[32:33], v[32:33], v[240:241] op_sel_hi:[1,0]
	v_pk_mul_f32 v[34:35], v[34:35], v[240:241] op_sel_hi:[1,0]
	v_pk_mul_f32 v[36:37], v[36:37], v[240:241] op_sel_hi:[1,0]
	v_pk_mul_f32 v[38:39], v[38:39], v[240:241] op_sel_hi:[1,0]
	v_pk_mul_f32 v[40:41], v[40:41], v[240:241] op_sel_hi:[1,0]
	v_pk_mul_f32 v[42:43], v[42:43], v[240:241] op_sel_hi:[1,0]
	v_pk_mul_f32 v[44:45], v[44:45], v[240:241] op_sel_hi:[1,0]
	v_pk_mul_f32 v[46:47], v[46:47], v[240:241] op_sel_hi:[1,0]
	v_pk_mul_f32 v[48:49], v[48:49], v[240:241] op_sel_hi:[1,0]
	v_pk_mul_f32 v[50:51], v[50:51], v[240:241] op_sel_hi:[1,0]
	v_pk_mul_f32 v[52:53], v[52:53], v[240:241] op_sel_hi:[1,0]
	v_pk_mul_f32 v[54:55], v[54:55], v[240:241] op_sel_hi:[1,0]
	v_pk_mul_f32 v[56:57], v[56:57], v[240:241] op_sel_hi:[1,0]
	v_pk_mul_f32 v[58:59], v[58:59], v[240:241] op_sel_hi:[1,0]
	v_pk_mul_f32 v[60:61], v[60:61], v[240:241] op_sel_hi:[1,0]
	v_pk_mul_f32 v[62:63], v[62:63], v[240:241] op_sel_hi:[1,0]
.Lat_k2:
	v_cvt_pk_bf16_f32 v64, v64, v65
	v_cvt_pk_bf16_f32 v65, v66, v67
	v_cvt_pk_bf16_f32 v66, v68, v69
	v_cvt_pk_bf16_f32 v67, v70, v71
	v_cvt_pk_bf16_f32 v68, v72, v73
	v_cvt_pk_bf16_f32 v69, v74, v75
	v_cvt_pk_bf16_f32 v70, v76, v77
	v_cvt_pk_bf16_f32 v71, v78, v79
	v_add_f32_e32 v234, v236, v237
	v_add_f32_e32 v207, v234, v207
	v_mov_b32_e32 v232, v238
	v_max_f32_e32 v234, v217, v217
	v_max_f32_e32 v235, v216, v216
	v_max_f32_e32 v234, v235, v234
	v_max3_f32 v234, v234, v218, v219
	v_max3_f32 v234, v234, v220, v221
	v_max3_f32 v234, v234, v222, v223
	v_max3_f32 v234, v234, v224, v225
	v_max3_f32 v234, v234, v226, v227
	v_max3_f32 v234, v234, v228, v229
	v_max3_f32 v234, v234, v230, v231
	v_mov_b32_e32 v235, v234
	s_nop 1
	v_permlane32_swap_b32_e32 v234, v235
	v_max_f32_e32 v235, v235, v235
	v_max_f32_e32 v234, v234, v234
	v_max_f32_e32 v234, v234, v235
	v_mul_f32_e32 v234, 0x3e38aa3b, v234
	v_add_f32_e32 v235, 0x41000000, v233
	v_cmp_gt_f32_e32 vcc, v234, v235
	s_nop 1
	v_cndmask_b32_e32 v238, v233, v234, vcc
	v_fma_f32 v216, v216, s77, -v238
	s_waitcnt lgkmcnt(0)
	v_mfma_f32_32x32x16_bf16 v[48:63], v[132:135], v[64:67], v[48:63]
	v_exp_f32_e32 v216, v216
	v_fma_f32 v217, v217, s77, -v238
	v_exp_f32_e32 v217, v217
	v_add_f32_e32 v236, 0, v216
	v_fma_f32 v218, v218, s77, -v238
	v_exp_f32_e32 v218, v218
	v_mfma_f32_32x32x16_bf16 v[32:47], v[124:127], v[64:67], v[32:47]
	v_add_f32_e32 v236, v217, v236
	v_fma_f32 v219, v219, s77, -v238
	v_exp_f32_e32 v219, v219
	v_add_f32_e32 v236, v218, v236
	v_fma_f32 v220, v220, s77, -v238
	v_exp_f32_e32 v220, v220
	v_mfma_f32_32x32x16_bf16 v[48:63], v[128:131], v[68:71], v[48:63]
	v_add_f32_e32 v236, v219, v236
	v_fma_f32 v221, v221, s77, -v238
	v_exp_f32_e32 v221, v221
	v_add_f32_e32 v236, v220, v236
	v_fma_f32 v222, v222, s77, -v238
	v_exp_f32_e32 v222, v222
	v_mfma_f32_32x32x16_bf16 v[32:47], v[120:123], v[68:71], v[32:47]
	v_add_f32_e32 v236, v221, v236
	v_fma_f32 v223, v223, s77, -v238
	v_exp_f32_e32 v223, v223
	v_add_f32_e32 v236, v222, v236
	v_fma_f32 v224, v224, s77, -v238
	v_exp_f32_e32 v224, v224
	v_add_f32_e32 v236, v223, v236
	v_fma_f32 v225, v225, s77, -v238
	v_exp_f32_e32 v225, v225
	v_add_f32_e32 v236, v224, v236
	v_fma_f32 v226, v226, s77, -v238
	v_exp_f32_e32 v226, v226
	v_add_f32_e32 v236, v225, v236
	v_fma_f32 v227, v227, s77, -v238
	v_exp_f32_e32 v227, v227
	v_add_f32_e32 v236, v226, v236
	v_fma_f32 v228, v228, s77, -v238
	v_exp_f32_e32 v228, v228
	v_add_f32_e32 v236, v227, v236
	v_fma_f32 v229, v229, s77, -v238
	v_exp_f32_e32 v229, v229
	v_add_f32_e32 v236, v228, v236
	v_fma_f32 v230, v230, s77, -v238
	v_exp_f32_e32 v230, v230
	v_add_f32_e32 v236, v229, v236
	v_fma_f32 v231, v231, s77, -v238
	v_exp_f32_e32 v231, v231
	v_add_f32_e32 v236, v230, v236
	v_cmp_neq_f32_e32 vcc, v238, v233
	v_add_f32_e32 v236, v231, v236
	v_mov_b32_e32 v237, v236
	s_nop 1
	v_permlane32_swap_b32_e32 v236, v237
	s_cbranch_vccz .Lat_k3
	v_sub_f32_e32 v240, v233, v238
	v_exp_f32_e32 v240, v240
	s_nop 0
	v_mul_f32_e32 v185, v185, v240
	v_pk_mul_f32 v[0:1], v[0:1], v[240:241] op_sel_hi:[1,0]
	v_pk_mul_f32 v[2:3], v[2:3], v[240:241] op_sel_hi:[1,0]
	v_pk_mul_f32 v[4:5], v[4:5], v[240:241] op_sel_hi:[1,0]
	v_pk_mul_f32 v[6:7], v[6:7], v[240:241] op_sel_hi:[1,0]
	v_pk_mul_f32 v[8:9], v[8:9], v[240:241] op_sel_hi:[1,0]
	v_pk_mul_f32 v[10:11], v[10:11], v[240:241] op_sel_hi:[1,0]
	v_pk_mul_f32 v[12:13], v[12:13], v[240:241] op_sel_hi:[1,0]
	v_pk_mul_f32 v[14:15], v[14:15], v[240:241] op_sel_hi:[1,0]
	v_pk_mul_f32 v[16:17], v[16:17], v[240:241] op_sel_hi:[1,0]
	v_pk_mul_f32 v[18:19], v[18:19], v[240:241] op_sel_hi:[1,0]
	v_pk_mul_f32 v[20:21], v[20:21], v[240:241] op_sel_hi:[1,0]
	v_pk_mul_f32 v[22:23], v[22:23], v[240:241] op_sel_hi:[1,0]
	v_pk_mul_f32 v[24:25], v[24:25], v[240:241] op_sel_hi:[1,0]
	v_pk_mul_f32 v[26:27], v[26:27], v[240:241] op_sel_hi:[1,0]
	v_pk_mul_f32 v[28:29], v[28:29], v[240:241] op_sel_hi:[1,0]
	v_pk_mul_f32 v[30:31], v[30:31], v[240:241] op_sel_hi:[1,0]
